# up-projection GEMM mainloop: LDS-DMA stages rebalanced 4+4 per load segment (A stage of K-step t+2 issued at the head of the next segment), retiring waits recounted
# speedup vs baseline: 1.0351x; 1.0037x over previous
.LBB0_68:
	s_add_u32 s8, s6, 0xfff80080
	s_addc_u32 s9, s7, -1
	s_add_i32 s33, 0, 0x10000
	s_cmp_eq_u32 s51, 28
	s_cselect_b32 s11, s21, s9
	s_cselect_b32 s10, s28, s8
	v_add_u32_e32 v16, s33, v190
	s_cselect_b32 s9, s19, s31
	s_cselect_b32 s8, s29, s30
	s_add_i32 s54, 0, 0x14000
	ds_read_b128 v[54:57], v16
	ds_read_b128 v[62:65], v16 offset:1024
	ds_read_b128 v[66:69], v16 offset:2048
	ds_read_b128 v[70:73], v16 offset:3072
	v_add_u32_e32 v16, s54, v190
	ds_read_b128 v[74:77], v16
	ds_read_b128 v[78:81], v16 offset:1024
	ds_read_b128 v[82:85], v16 offset:2048
	ds_read_b128 v[86:89], v16 offset:3072
	s_cmp_eq_u32 s51, -2
	s_cbranch_scc1 .Lup_skipA10
	v_lshl_add_u64 v[214:215], v[236:237], 0, s[56:57]
	s_mov_b32 m0, s46
	s_nop 0
	global_load_lds_dwordx4 v[214:215], off
	v_lshl_add_u64 v[214:215], v[238:239], 0, s[56:57]
	s_mov_b32 m0, s47
	s_nop 0
	global_load_lds_dwordx4 v[214:215], off
.Lup_skipA10:
	v_lshl_add_u64 v[214:215], s[6:7], 0, v[180:181]
	s_add_i32 m0, s41, 0xc000
	ds_read_b128 v[170:173], v192
	ds_read_b128 v[184:187], v192 offset:1024
	ds_read_b128 v[194:197], v192 offset:2048
	ds_read_b128 v[198:201], v192 offset:3072
	ds_read_b128 v[202:205], v192 offset:4096
	ds_read_b128 v[206:209], v192 offset:5120
	ds_read_b128 v[210:213], v192 offset:6144
	ds_read_b128 v[222:225], v192 offset:7168
	global_load_lds_dwordx4 v[214:215], off
	v_lshl_add_u64 v[214:215], s[6:7], 0, v[182:183]
	s_add_i32 m0, s41, 0xe000
	s_nop 0
	global_load_lds_dwordx4 v[214:215], off
	s_waitcnt vmcnt(8)
	s_waitcnt lgkmcnt(0)
	s_barrier
	s_setprio 1
	s_waitcnt lgkmcnt(0)
	v_mfma_f32_16x16x32_bf16 v[150:153], v[54:57], v[170:173], v[150:153]
	v_mfma_f32_16x16x32_bf16 v[142:145], v[66:69], v[170:173], v[142:145]
	v_mfma_f32_16x16x32_bf16 v[134:137], v[54:57], v[194:197], v[134:137]
	v_mfma_f32_16x16x32_bf16 v[126:129], v[66:69], v[194:197], v[126:129]
	v_mfma_f32_16x16x32_bf16 v[118:121], v[54:57], v[202:205], v[118:121]
	v_mfma_f32_16x16x32_bf16 v[114:117], v[66:69], v[202:205], v[114:117]
	v_mfma_f32_16x16x32_bf16 v[110:113], v[54:57], v[210:213], v[110:113]
	v_mfma_f32_16x16x32_bf16 v[106:109], v[66:69], v[210:213], v[106:109]
	v_mfma_f32_16x16x32_bf16 v[150:153], v[62:65], v[184:187], v[150:153]
	v_mfma_f32_16x16x32_bf16 v[142:145], v[70:73], v[184:187], v[142:145]
	v_mfma_f32_16x16x32_bf16 v[134:137], v[62:65], v[198:201], v[134:137]
	v_mfma_f32_16x16x32_bf16 v[126:129], v[70:73], v[198:201], v[126:129]
	v_mfma_f32_16x16x32_bf16 v[118:121], v[62:65], v[206:209], v[118:121]
	v_mfma_f32_16x16x32_bf16 v[114:117], v[70:73], v[206:209], v[114:117]
	v_mfma_f32_16x16x32_bf16 v[110:113], v[62:65], v[222:225], v[110:113]
	v_mfma_f32_16x16x32_bf16 v[106:109], v[70:73], v[222:225], v[106:109]
	s_setprio 0
	s_setprio 1
	v_mfma_f32_16x16x32_bf16 v[158:161], v[74:77], v[170:173], v[158:161]
	v_mfma_f32_16x16x32_bf16 v[154:157], v[82:85], v[170:173], v[154:157]
	v_mfma_f32_16x16x32_bf16 v[146:149], v[74:77], v[194:197], v[146:149]
	v_mfma_f32_16x16x32_bf16 v[138:141], v[82:85], v[194:197], v[138:141]
	v_mfma_f32_16x16x32_bf16 v[130:133], v[74:77], v[202:205], v[130:133]
	v_mfma_f32_16x16x32_bf16 v[122:125], v[82:85], v[202:205], v[122:125]
	v_mfma_f32_16x16x32_bf16 v[102:105], v[74:77], v[210:213], v[102:105]
	v_mfma_f32_16x16x32_bf16 v[98:101], v[82:85], v[210:213], v[98:101]
	v_mfma_f32_16x16x32_bf16 v[158:161], v[78:81], v[184:187], v[158:161]
	v_mfma_f32_16x16x32_bf16 v[154:157], v[86:89], v[184:187], v[154:157]
	v_mfma_f32_16x16x32_bf16 v[146:149], v[78:81], v[198:201], v[146:149]
	v_mfma_f32_16x16x32_bf16 v[138:141], v[86:89], v[198:201], v[138:141]
	v_mfma_f32_16x16x32_bf16 v[130:133], v[78:81], v[206:209], v[130:133]
	v_mfma_f32_16x16x32_bf16 v[122:125], v[86:89], v[206:209], v[122:125]
	v_mfma_f32_16x16x32_bf16 v[102:105], v[78:81], v[222:225], v[102:105]
	v_mfma_f32_16x16x32_bf16 v[98:101], v[86:89], v[222:225], v[98:101]
	s_setprio 0
	s_barrier
	s_add_i32 s33, s33, s38
	v_lshl_add_u64 v[214:215], s[8:9], 0, v[166:167]
	s_mov_b32 m0, s33
	ds_read_b128 v[170:173], v192 offset:16384
	ds_read_b128 v[184:187], v192 offset:17408
	ds_read_b128 v[194:197], v192 offset:18432
	ds_read_b128 v[198:201], v192 offset:19456
	ds_read_b128 v[202:205], v192 offset:20480
	ds_read_b128 v[206:209], v192 offset:21504
	ds_read_b128 v[210:213], v192 offset:22528
	ds_read_b128 v[222:225], v192 offset:23552
	global_load_lds_dwordx4 v[214:215], off
	s_add_i32 m0, s33, 0x2000
	s_add_u32 s52, s8, 0x80000
	v_lshl_add_u64 v[234:235], s[8:9], 0, v[162:163]
	s_addc_u32 s53, s9, 0
	s_add_i32 s33, s54, s38
	global_load_lds_dwordx4 v[234:235], off
	v_lshl_add_u64 v[230:231], s[52:53], 0, v[166:167]
	s_mov_b32 m0, s33
	v_lshl_add_u64 v[236:237], s[10:11], 0, v[168:169]
	global_load_lds_dwordx4 v[230:231], off
	v_lshl_add_u64 v[230:231], s[52:53], 0, v[162:163]
	s_add_i32 m0, s33, 0x2000
	v_lshl_add_u64 v[238:239], s[10:11], 0, v[164:165]
	global_load_lds_dwordx4 v[230:231], off
	s_waitcnt vmcnt(6)
	s_waitcnt lgkmcnt(0)
	s_barrier
	s_setprio 1
	s_waitcnt lgkmcnt(0)
	v_mfma_f32_16x16x32_bf16 v[58:61], v[54:57], v[170:173], v[58:61]
	v_mfma_f32_16x16x32_bf16 v[46:49], v[66:69], v[170:173], v[46:49]
	v_mfma_f32_16x16x32_bf16 v[38:41], v[54:57], v[194:197], v[38:41]
	v_mfma_f32_16x16x32_bf16 v[30:33], v[66:69], v[194:197], v[30:33]
	v_mfma_f32_16x16x32_bf16 v[22:25], v[54:57], v[202:205], v[22:25]
	v_mfma_f32_16x16x32_bf16 v[18:21], v[66:69], v[202:205], v[18:21]
	v_mfma_f32_16x16x32_bf16 v[8:11], v[54:57], v[210:213], v[8:11]
	v_mfma_f32_16x16x32_bf16 v[12:15], v[66:69], v[210:213], v[12:15]
	v_mfma_f32_16x16x32_bf16 v[58:61], v[62:65], v[184:187], v[58:61]
	v_mfma_f32_16x16x32_bf16 v[46:49], v[70:73], v[184:187], v[46:49]
	v_mfma_f32_16x16x32_bf16 v[38:41], v[62:65], v[198:201], v[38:41]
	v_mfma_f32_16x16x32_bf16 v[30:33], v[70:73], v[198:201], v[30:33]
	v_mfma_f32_16x16x32_bf16 v[22:25], v[62:65], v[206:209], v[22:25]
	v_mfma_f32_16x16x32_bf16 v[18:21], v[70:73], v[206:209], v[18:21]
	v_mfma_f32_16x16x32_bf16 v[8:11], v[62:65], v[222:225], v[8:11]
	v_mfma_f32_16x16x32_bf16 v[12:15], v[70:73], v[222:225], v[12:15]
	s_setprio 0
	s_setprio 1
	v_mfma_f32_16x16x32_bf16 v[50:53], v[74:77], v[194:197], v[50:53]
	v_mfma_f32_16x16x32_bf16 v[42:45], v[82:85], v[194:197], v[42:45]
	v_mfma_f32_16x16x32_bf16 v[34:37], v[74:77], v[202:205], v[34:37]
	v_mfma_f32_16x16x32_bf16 v[26:29], v[82:85], v[202:205], v[26:29]
	v_mfma_f32_16x16x32_bf16 v[0:3], v[74:77], v[210:213], v[0:3]
	v_mfma_f32_16x16x32_bf16 v[4:7], v[82:85], v[210:213], v[4:7]
	v_mfma_f32_16x16x32_bf16 v[54:57], v[74:77], v[170:173], v[94:97]
	v_mfma_f32_16x16x32_bf16 v[62:65], v[82:85], v[170:173], v[90:93]
	v_mfma_f32_16x16x32_bf16 v[50:53], v[78:81], v[198:201], v[50:53]
	v_mfma_f32_16x16x32_bf16 v[42:45], v[86:89], v[198:201], v[42:45]
	v_mfma_f32_16x16x32_bf16 v[34:37], v[78:81], v[206:209], v[34:37]
	v_mfma_f32_16x16x32_bf16 v[26:29], v[86:89], v[206:209], v[26:29]
	v_mfma_f32_16x16x32_bf16 v[0:3], v[78:81], v[222:225], v[0:3]
	v_mfma_f32_16x16x32_bf16 v[4:7], v[86:89], v[222:225], v[4:7]
	v_mfma_f32_16x16x32_bf16 v[54:57], v[78:81], v[184:187], v[54:57]
	v_mfma_f32_16x16x32_bf16 v[62:65], v[86:89], v[184:187], v[62:65]
	s_setprio 0
	s_barrier
	s_add_i32 s33, 0, 0x18000
	v_add_u32_e32 v16, s33, v190
	s_add_i32 s52, 0, 0x1c000
	ds_read_b128 v[66:69], v16
	ds_read_b128 v[70:73], v16 offset:1024
	ds_read_b128 v[74:77], v16 offset:2048
	ds_read_b128 v[78:81], v16 offset:3072
	v_add_u32_e32 v16, s52, v190
	ds_read_b128 v[82:85], v16
	ds_read_b128 v[86:89], v16 offset:1024
	ds_read_b128 v[170:173], v16 offset:2048
	ds_read_b128 v[184:187], v16 offset:3072
	s_mov_b32 m0, s41
	s_nop 0
	global_load_lds_dwordx4 v[236:237], off
	s_mov_b32 m0, s42
	s_nop 0
	global_load_lds_dwordx4 v[238:239], off
	s_add_u32 s10, s10, 0x80000
	s_addc_u32 s11, s11, 0
	s_mov_b32 m0, s43
	v_lshl_add_u64 v[230:231], s[10:11], 0, v[168:169]
	ds_read_b128 v[90:93], v192 offset:32768
	ds_read_b128 v[94:97], v192 offset:33792
	ds_read_b128 v[194:197], v192 offset:34816
	ds_read_b128 v[198:201], v192 offset:35840
	ds_read_b128 v[202:205], v192 offset:36864
	ds_read_b128 v[206:209], v192 offset:37888
	ds_read_b128 v[210:213], v192 offset:38912
	ds_read_b128 v[222:225], v192 offset:39936
	global_load_lds_dwordx4 v[230:231], off
	v_lshl_add_u64 v[230:231], s[10:11], 0, v[164:165]
	s_mov_b32 m0, s44
	s_nop 0
	global_load_lds_dwordx4 v[230:231], off
	s_waitcnt vmcnt(8)
	s_waitcnt lgkmcnt(0)
	s_barrier
	s_setprio 1
	s_waitcnt lgkmcnt(0)
	v_mfma_f32_16x16x32_bf16 v[150:153], v[66:69], v[90:93], v[150:153]
	v_mfma_f32_16x16x32_bf16 v[142:145], v[74:77], v[90:93], v[142:145]
	v_mfma_f32_16x16x32_bf16 v[134:137], v[66:69], v[194:197], v[134:137]
	v_mfma_f32_16x16x32_bf16 v[126:129], v[74:77], v[194:197], v[126:129]
	v_mfma_f32_16x16x32_bf16 v[118:121], v[66:69], v[202:205], v[118:121]
	v_mfma_f32_16x16x32_bf16 v[114:117], v[74:77], v[202:205], v[114:117]
	v_mfma_f32_16x16x32_bf16 v[110:113], v[66:69], v[210:213], v[110:113]
	v_mfma_f32_16x16x32_bf16 v[106:109], v[74:77], v[210:213], v[106:109]
	v_mfma_f32_16x16x32_bf16 v[150:153], v[70:73], v[94:97], v[150:153]
	v_mfma_f32_16x16x32_bf16 v[142:145], v[78:81], v[94:97], v[142:145]
	v_mfma_f32_16x16x32_bf16 v[134:137], v[70:73], v[198:201], v[134:137]
	v_mfma_f32_16x16x32_bf16 v[126:129], v[78:81], v[198:201], v[126:129]
	v_mfma_f32_16x16x32_bf16 v[118:121], v[70:73], v[206:209], v[118:121]
	v_mfma_f32_16x16x32_bf16 v[114:117], v[78:81], v[206:209], v[114:117]
	v_mfma_f32_16x16x32_bf16 v[110:113], v[70:73], v[222:225], v[110:113]
	v_mfma_f32_16x16x32_bf16 v[106:109], v[78:81], v[222:225], v[106:109]
	s_setprio 0
	s_setprio 1
	v_mfma_f32_16x16x32_bf16 v[158:161], v[82:85], v[90:93], v[158:161]
	v_mfma_f32_16x16x32_bf16 v[90:93], v[170:173], v[90:93], v[154:157]
	v_mfma_f32_16x16x32_bf16 v[154:157], v[184:187], v[94:97], v[90:93]
	v_mfma_f32_16x16x32_bf16 v[90:93], v[82:85], v[194:197], v[146:149]
	v_mfma_f32_16x16x32_bf16 v[146:149], v[86:89], v[198:201], v[90:93]
	v_mfma_f32_16x16x32_bf16 v[90:93], v[170:173], v[194:197], v[138:141]
	v_mfma_f32_16x16x32_bf16 v[138:141], v[184:187], v[198:201], v[90:93]
	v_mfma_f32_16x16x32_bf16 v[90:93], v[82:85], v[202:205], v[130:133]
	v_mfma_f32_16x16x32_bf16 v[130:133], v[86:89], v[206:209], v[90:93]
	v_mfma_f32_16x16x32_bf16 v[90:93], v[170:173], v[202:205], v[122:125]
	v_mfma_f32_16x16x32_bf16 v[122:125], v[184:187], v[206:209], v[90:93]
	v_mfma_f32_16x16x32_bf16 v[90:93], v[82:85], v[210:213], v[102:105]
	v_mfma_f32_16x16x32_bf16 v[102:105], v[86:89], v[222:225], v[90:93]
	v_mfma_f32_16x16x32_bf16 v[90:93], v[170:173], v[210:213], v[98:101]
	v_mfma_f32_16x16x32_bf16 v[158:161], v[86:89], v[94:97], v[158:161]
	v_mfma_f32_16x16x32_bf16 v[98:101], v[184:187], v[222:225], v[90:93]
	s_setprio 0
	s_barrier
	s_add_i32 s10, s33, s38
	v_lshl_add_u64 v[94:95], v[214:215], 0, s[56:57]
	s_mov_b32 m0, s10
	s_nop 0
	ds_read_b128 v[90:93], v192 offset:49152
	ds_read_b128 v[194:197], v192 offset:50176
	ds_read_b128 v[198:201], v192 offset:51200
	ds_read_b128 v[202:205], v192 offset:52224
	ds_read_b128 v[206:209], v192 offset:53248
	ds_read_b128 v[210:213], v192 offset:54272
	ds_read_b128 v[222:225], v192 offset:55296
	ds_read_b128 v[230:233], v192 offset:56320
	global_load_lds_dwordx4 v[94:95], off
	s_add_i32 m0, s10, 0x2000
	s_add_u32 s8, s8, 0x80080
	v_lshl_add_u64 v[94:95], v[234:235], 0, s[56:57]
	s_addc_u32 s9, s9, 0
	s_add_i32 s10, s52, s38
	global_load_lds_dwordx4 v[94:95], off
	v_lshl_add_u64 v[94:95], s[8:9], 0, v[166:167]
	s_mov_b32 m0, s10
	s_nop 0
	global_load_lds_dwordx4 v[94:95], off
	v_lshl_add_u64 v[94:95], s[8:9], 0, v[162:163]
	s_add_i32 m0, s10, 0x2000
	s_nop 0
	global_load_lds_dwordx4 v[94:95], off
	s_cmp_eq_u32 s51, 28
	s_cbranch_scc0 .Lup_notlast
	v_lshl_add_u64 v[94:95], v[236:237], 0, s[56:57]
	s_mov_b32 m0, s46
	s_nop 0
	global_load_lds_dwordx4 v[94:95], off
	v_lshl_add_u64 v[94:95], v[238:239], 0, s[56:57]
	s_mov_b32 m0, s47
	s_nop 0
	global_load_lds_dwordx4 v[94:95], off
	s_waitcnt vmcnt(8)
	s_branch .Lup_join
.Lup_notlast:
	s_waitcnt vmcnt(6)
.Lup_join:
	s_waitcnt lgkmcnt(0)
	s_barrier
	s_setprio 1
	s_waitcnt lgkmcnt(0)
	v_mfma_f32_16x16x32_bf16 v[58:61], v[66:69], v[90:93], v[58:61]
	v_mfma_f32_16x16x32_bf16 v[46:49], v[74:77], v[90:93], v[46:49]
	v_mfma_f32_16x16x32_bf16 v[38:41], v[66:69], v[198:201], v[38:41]
	v_mfma_f32_16x16x32_bf16 v[30:33], v[74:77], v[198:201], v[30:33]
	v_mfma_f32_16x16x32_bf16 v[22:25], v[66:69], v[206:209], v[22:25]
	v_mfma_f32_16x16x32_bf16 v[18:21], v[74:77], v[206:209], v[18:21]
	v_mfma_f32_16x16x32_bf16 v[8:11], v[66:69], v[222:225], v[8:11]
	v_mfma_f32_16x16x32_bf16 v[12:15], v[74:77], v[222:225], v[12:15]
	v_mfma_f32_16x16x32_bf16 v[58:61], v[70:73], v[194:197], v[58:61]
	v_mfma_f32_16x16x32_bf16 v[46:49], v[78:81], v[194:197], v[46:49]
	v_mfma_f32_16x16x32_bf16 v[38:41], v[70:73], v[202:205], v[38:41]
	v_mfma_f32_16x16x32_bf16 v[30:33], v[78:81], v[202:205], v[30:33]
	v_mfma_f32_16x16x32_bf16 v[22:25], v[70:73], v[210:213], v[22:25]
	v_mfma_f32_16x16x32_bf16 v[18:21], v[78:81], v[210:213], v[18:21]
	v_mfma_f32_16x16x32_bf16 v[8:11], v[70:73], v[230:233], v[8:11]
	v_mfma_f32_16x16x32_bf16 v[12:15], v[78:81], v[230:233], v[12:15]
	s_setprio 0
	s_setprio 1
	v_mfma_f32_16x16x32_bf16 v[54:57], v[82:85], v[90:93], v[54:57]
	v_mfma_f32_16x16x32_bf16 v[94:97], v[86:89], v[194:197], v[54:57]
	v_mfma_f32_16x16x32_bf16 v[54:57], v[170:173], v[90:93], v[62:65]
	v_mfma_f32_16x16x32_bf16 v[50:53], v[82:85], v[198:201], v[50:53]
	v_mfma_f32_16x16x32_bf16 v[42:45], v[170:173], v[198:201], v[42:45]
	v_mfma_f32_16x16x32_bf16 v[34:37], v[82:85], v[206:209], v[34:37]
	v_mfma_f32_16x16x32_bf16 v[26:29], v[170:173], v[206:209], v[26:29]
	v_mfma_f32_16x16x32_bf16 v[0:3], v[82:85], v[222:225], v[0:3]
	v_mfma_f32_16x16x32_bf16 v[4:7], v[170:173], v[222:225], v[4:7]
	v_mfma_f32_16x16x32_bf16 v[90:93], v[184:187], v[194:197], v[54:57]
	v_mfma_f32_16x16x32_bf16 v[50:53], v[86:89], v[202:205], v[50:53]
	v_mfma_f32_16x16x32_bf16 v[42:45], v[184:187], v[202:205], v[42:45]
	v_mfma_f32_16x16x32_bf16 v[34:37], v[86:89], v[210:213], v[34:37]
	v_mfma_f32_16x16x32_bf16 v[26:29], v[184:187], v[210:213], v[26:29]
	v_mfma_f32_16x16x32_bf16 v[0:3], v[86:89], v[230:233], v[0:3]
	v_mfma_f32_16x16x32_bf16 v[4:7], v[184:187], v[230:233], v[4:7]
	s_setprio 0
	s_barrier
	s_add_i32 s51, s51, 2
	s_add_u32 s6, s6, 0x100
	s_addc_u32 s7, s7, 0
	s_add_u32 s30, s30, 0x100
	s_addc_u32 s31, s31, 0
	s_cmp_gt_u32 s51, 29
	s_cbranch_scc0 .LBB0_68
	s_and_b64 vcc, exec, s[16:17]
	s_cbranch_vccz .LBB0_71
	s_barrier
